# LN GEMM phases: first unit's residual tile touched (L2 prefetch) by waves 1-4 while the workgroup waits in the preceding grid barrier
# baseline (speedup 1.0000x reference)
.LBB0_1697:
	s_or_b64 exec, exec, s[2:3]
	s_branch .LBB0_1698
.Lpf_a:
	v_readlane_b32 s32, v252, 23
	s_nop 3
	s_sub_u32 s32, s32, 1
	s_cmp_gt_u32 s32, 3
	s_cbranch_scc1 .LBB0_1698
	v_mbcnt_lo_u32_b32 v210, -1, 0
	v_mbcnt_hi_u32_b32 v210, -1, v210
	s_lshl_b32 s32, s32, 6
	v_add_u32_e32 v210, s32, v210
	v_lshlrev_b32_e32 v210, 11, v210
	v_readlane_b32 s100, v254, 19
	v_readlane_b32 s32, v254, 18
	s_nop 3
	s_lshl_b32 s100, s100, 19
	s_lshl_b32 s32, s32, 9
	s_add_u32 s100, s100, s32
	s_add_u32 s100, s10, s100
	s_addc_u32 s101, s11, 0
	global_load_dword v211, v210, s[100:101]
	global_load_dword v211, v210, s[100:101] offset:128
	global_load_dword v211, v210, s[100:101] offset:256
	global_load_dword v211, v210, s[100:101] offset:384

.LBB0_1958:
	s_or_b64 exec, exec, s[16:17]
	s_branch .LBB0_1959
